# P8/P9/P11 epilogues: touch the second half's residual/gate lines while the first half's loads are in flight
# speedup vs baseline: 1.0050x; 1.0050x over previous
; DI v4u pack8(const f4& a, const f4& b) { v4u w; w.x = cvt_pk_bf16(a[0], a[1]); w.y = cvt_pk_bf16(a[2], a[3]); w.z = cvt_pk_bf16(b[0], b[1]); w.w = cvt_pk_bf16(b[2], b[3]); return w; }
; DI void unpack8(const v4u& w, f4& a, f4& b) { a[0] = bf_lo(w.x); a[1] = bf_hi(w.x); a[2] = bf_lo(w.y); a[3] = bf_hi(w.y); b[0] = bf_lo(w.z); b[1] = bf_hi(w.z); b[2] = bf_lo(w.w); b[3] = bf_hi(w.w); }
;     DI void operator()(f4 (&acc)[2][2][4][2], const Unit& u, int wr, int wc, int fr, int fq) const {
;     ...
;         const int which = u.pm >> 6, row0 = (u.pm & 63) * BM + wr * 64 + fr, col0 = (u.pn & 15) * BM + wc * 32 + 8 * fq;
;         const bf16* gsrc = gates + (which ? (size_t)M * D : (size_t)0);
; #pragma unroll
;         for (int ai = 0; ai < 2; ++ai) {
;             v4u gv[4][2];
; #pragma unroll
;             for (int m = 0; m < 4; ++m)
; #pragma unroll
;                 for (int bj = 0; bj < 2; ++bj) gv[m][bj] = *(const v4u*)(gsrc + (size_t)(row0 + ai * HALF + m * 16) * D + col0 + bj * HALF);
;             asm volatile("" ::: "memory");
; #pragma unroll
;             for (int m = 0; m < 4; ++m) { const int row = row0 + ai * HALF + m * 16;
; #pragma unroll
;                 for (int bj = 0; bj < 2; ++bj) { f4 g0, g1; unpack8(gv[m][bj], g0, g1);
;                     if (which == 0) { acc[ai][bj][m][0] = acc[ai][bj][m][0] * g0; acc[ai][bj][m][1] = acc[ai][bj][m][1] * g1; }
;                     else *(v4u*)(mout + (size_t)row * D + col0 + bj * HALF) = pack8(acc[ai][bj][m][0] * g0, acc[ai][bj][m][1] * g1); } }
.LBB0_2607:
	s_lshl_b32 s7, s12, 8
	s_lshl_b32 s6, s6, 8
	s_and_b32 s7, s7, 0x3f00
	s_and_b32 s6, s6, 0xf00
	v_mbcnt_lo_u32_b32 v2, -1, 0
	v_mbcnt_hi_u32_b32 v2, -1, v2
	s_add_i32 s7, s7, s41
	s_or_b32 s6, s6, s42
	v_and_or_b32 v0, v2, 15, s7
	v_ashrrev_i32_e32 v2, 1, v2
	s_cmp_gt_u32 s12, 63
	v_and_b32_e32 v2, -8, v2
	s_cselect_b64 s[24:25], -1, 0
	s_cmp_lt_u32 s12, 64
	v_add_u32_e32 v2, s6, v2
	s_cselect_b64 s[6:7], -1, 0
	s_and_b64 vcc, s[6:7], exec
	s_cselect_b32 s6, 0, 0x8000000
	s_add_u32 s6, s39, s6
	s_addc_u32 s7, s40, 0
	v_ashrrev_i32_e32 v3, 31, v2
	v_lshl_add_u64 v[184:185], v[2:3], 1, s[6:7]
	v_lshlrev_b64 v[64:65], 13, v[0:1]
	v_lshl_add_u64 v[66:67], v[184:185], 0, v[64:65]
	s_mov_b64 s[98:99], 0x100000
	v_lshl_add_u64 v[226:227], v[66:67], 0, s[98:99]
	global_load_dword v228, v[226:227], off
	global_load_dword v229, v[226:227], off offset:256
	global_load_dwordx4 v[60:63], v[66:67], off
	global_load_dwordx4 v[88:91], v[66:67], off offset:256
	v_or_b32_e32 v66, 16, v0
	v_mov_b32_e32 v67, v1
	v_lshlrev_b64 v[190:191], 13, v[66:67]
	v_lshl_add_u64 v[66:67], v[184:185], 0, v[190:191]
	v_lshl_add_u64 v[226:227], v[66:67], 0, s[98:99]
	global_load_dword v230, v[226:227], off
	global_load_dword v231, v[226:227], off offset:256
	global_load_dwordx4 v[84:87], v[66:67], off
	global_load_dwordx4 v[120:123], v[66:67], off offset:256
	v_or_b32_e32 v66, 32, v0
	v_mov_b32_e32 v67, v1
	v_lshlrev_b64 v[188:189], 13, v[66:67]
	v_lshl_add_u64 v[66:67], v[184:185], 0, v[188:189]
	v_lshl_add_u64 v[226:227], v[66:67], 0, s[98:99]
	global_load_dword v232, v[226:227], off
	global_load_dword v233, v[226:227], off offset:256
	global_load_dwordx4 v[116:119], v[66:67], off
	global_load_dwordx4 v[144:147], v[66:67], off offset:256
	v_or_b32_e32 v66, 48, v0
	v_mov_b32_e32 v67, v1
	v_lshlrev_b64 v[186:187], 13, v[66:67]
	v_lshl_add_u64 v[66:67], v[184:185], 0, v[186:187]
	v_lshl_add_u64 v[226:227], v[66:67], 0, s[98:99]
	global_load_dword v234, v[226:227], off
	global_load_dword v235, v[226:227], off offset:256
	global_load_dwordx4 v[140:143], v[66:67], off
	global_load_dwordx4 v[164:167], v[66:67], off offset:256
	v_lshl_add_u64 v[64:65], s[8:9], 0, v[64:65]
	v_lshl_add_u64 v[192:193], v[2:3], 1, v[64:65]
	s_waitcnt vmcnt(0)
	v_lshlrev_b32_e32 v64, 16, v60
	v_and_b32_e32 v65, 0xffff0000, v60
	v_lshlrev_b32_e32 v60, 16, v61
	v_and_b32_e32 v61, 0xffff0000, v61
	v_lshlrev_b32_e32 v196, 16, v62
	v_and_b32_e32 v197, 0xffff0000, v62
	v_lshlrev_b32_e32 v62, 16, v63
	v_and_b32_e32 v63, 0xffff0000, v63
	v_pk_mul_f32 v[66:67], v[82:83], v[60:61]
	v_pk_mul_f32 v[64:65], v[80:81], v[64:65]
	v_pk_mul_f32 v[62:63], v[78:79], v[62:63]
	v_pk_mul_f32 v[60:61], v[76:77], v[196:197]
	s_cbranch_vccnz .LBB0_2609
	v_cvt_pk_bf16_f32 v64, v64, v65
	v_cvt_pk_bf16_f32 v65, v66, v67
	v_cvt_pk_bf16_f32 v66, v60, v61
	v_cvt_pk_bf16_f32 v67, v62, v63
	global_store_dwordx4 v[192:193], v[64:67], off
	v_mov_b64_e32 v[60:61], v[76:77]
	v_mov_b64_e32 v[62:63], v[78:79]
	v_mov_b64_e32 v[64:65], v[80:81]
	v_mov_b64_e32 v[66:67], v[82:83]

; __device__ __forceinline__ int lane_opaque() { int l; asm volatile("v_mbcnt_lo_u32_b32 %0, -1, 0\n\tv_mbcnt_hi_u32_b32 %0, -1, %0" : "=v"(l)); return l; }
; DI v4u pack8(const f4& a, const f4& b) { v4u w; w.x = cvt_pk_bf16(a[0], a[1]); w.y = cvt_pk_bf16(a[2], a[3]); w.z = cvt_pk_bf16(b[0], b[1]); w.w = cvt_pk_bf16(b[2], b[3]); return w; }
;     DI void operator()(f4 (&acc)[2][2][4][2], const Unit& u, int wr, int wc, int fr, int fq) const {
;         { const int ln_ = lane_opaque(); fr = ln_ & 15; fq = ln_ >> 4; }
;         const int row0 = u.pm * BM + wr * 64 + fr, col0 = u.pn * BM + wc * 32 + 8 * fq;
; #pragma unroll
;         for (int ai = 0; ai < 2; ++ai) {
;             f4 b0[4][2], b1[4][2];
;             if constexpr (SRCB) {
;                 v4u bb[4][2];
; #pragma unroll
;                 for (int m = 0; m < 4; ++m)
; #pragma unroll
;                     for (int bj = 0; bj < 2; ++bj) bb[m][bj] = *(const v4u*)(baseb + (size_t)(row0 + ai * HALF + m * 16) * D + col0 + bj * HALF);
;                 asm volatile("" ::: "memory");
; #pragma unroll
;                 for (int m = 0; m < 4; ++m)
; #pragma unroll
;                     for (int bj = 0; bj < 2; ++bj) unpack8(bb[m][bj], b0[m][bj], b1[m][bj]);
;             } else {
; #pragma unroll
;                 for (int m = 0; m < 4; ++m)
; #pragma unroll
;                     for (int bj = 0; bj < 2; ++bj) { const size_t off = (size_t)(row0 + ai * HALF + m * 16) * D + col0 + bj * HALF; b0[m][bj] = *(const f4*)(base + off); b1[m][bj] = *(const f4*)(base + off + 4); }
;                 asm volatile("" ::: "memory");
;             }
; #pragma unroll
;             for (int m = 0; m < 4; ++m) { const int row = row0 + ai * HALF + m * 16; float s = 0.f;
; #pragma unroll
;                 for (int bj = 0; bj < 2; ++bj) { const size_t off = (size_t)row * D + col0 + bj * HALF;
;                     const f4 h0 = b0[m][bj] + acc[ai][bj][m][0], h1 = b1[m][bj] + acc[ai][bj][m][1];
;                     *(v4u*)(outb + off) = pack8(h0, h1);
;                     s += (h0[0] * h0[0] + h0[1] * h0[1]) + (h0[2] * h0[2] + h0[3] * h0[3]) + (h1[0] * h1[0] + h1[1] * h1[1]) + (h1[2] * h1[2] + h1[3] * h1[3]); }
;                 s += __shfl_xor(s, 16); s += __shfl_xor(s, 32);
;                 if (fq == 0) atomicAdd(ss + row, s); }
.LBB0_2720:
	v_mbcnt_lo_u32_b32 v191, -1, 0
	v_mbcnt_hi_u32_b32 v191, -1, v191
	s_lshl_b32 s0, s0, 8
	v_ashrrev_i32_e32 v128, 1, v191
	s_lshl_b32 s1, s26, 8
	s_or_b32 s0, s0, s45
	v_and_b32_e32 v128, -8, v128
	s_add_i32 s1, s1, s44
	v_add_u32_e32 v168, s0, v128
	v_and_or_b32 v172, v191, 15, s1
	v_ashrrev_i32_e32 v169, 31, v168
	v_lshlrev_b64 v[200:201], 1, v[168:169]
	v_ashrrev_i32_e32 v173, 31, v172
	v_lshl_add_u64 v[170:171], s[6:7], 0, v[200:201]
	v_lshlrev_b64 v[202:203], 13, v[172:173]
	v_lshl_add_u64 v[128:129], v[170:171], 0, v[202:203]
	s_mov_b64 s[98:99], 0x100000
	v_lshl_add_u64 v[226:227], v[128:129], 0, s[98:99]
	global_load_dword v228, v[226:227], off
	global_load_dword v229, v[226:227], off offset:256
	global_load_dwordx4 v[192:195], v[128:129], off
	global_load_dwordx4 v[196:199], v[128:129], off offset:256
	v_or_b32_e32 v182, 16, v172
	v_or_b32_e32 v178, 32, v172
	v_or_b32_e32 v174, 48, v172
	v_ashrrev_i32_e32 v183, 31, v182
	v_ashrrev_i32_e32 v179, 31, v178
	v_ashrrev_i32_e32 v175, 31, v174
	v_lshlrev_b64 v[184:185], 13, v[182:183]
	v_lshlrev_b64 v[180:181], 13, v[178:179]
	v_lshlrev_b64 v[176:177], 13, v[174:175]
	v_lshl_add_u64 v[128:129], v[170:171], 0, v[184:185]
	v_lshl_add_u64 v[130:131], v[170:171], 0, v[180:181]
	v_lshl_add_u64 v[204:205], v[170:171], 0, v[176:177]
	v_lshl_add_u64 v[226:227], v[128:129], 0, s[98:99]
	global_load_dword v230, v[226:227], off
	global_load_dword v231, v[226:227], off offset:256
	global_load_dwordx4 v[148:151], v[128:129], off
	global_load_dwordx4 v[144:147], v[128:129], off offset:256
	v_lshl_add_u64 v[226:227], v[130:131], 0, s[98:99]
	global_load_dword v232, v[226:227], off
	global_load_dword v233, v[226:227], off offset:256
	global_load_dwordx4 v[140:143], v[130:131], off
	global_load_dwordx4 v[136:139], v[130:131], off offset:256
	v_lshl_add_u64 v[226:227], v[204:205], 0, s[98:99]
	global_load_dword v234, v[226:227], off
	global_load_dword v235, v[226:227], off offset:256
	global_load_dwordx4 v[132:135], v[204:205], off
	s_nop 0
	global_load_dwordx4 v[128:131], v[204:205], off offset:256
	v_and_b32_e32 v205, 64, v190
	v_xor_b32_e32 v204, 16, v190
	v_add_u32_e32 v211, 64, v205
	v_lshl_add_u64 v[202:203], s[10:11], 0, v[202:203]
	v_cmp_lt_i32_e64 s[0:1], v204, v211
	v_lshl_add_u64 v[200:201], v[202:203], 0, v[200:201]
	v_cmp_gt_u32_e32 vcc, 16, v191
	v_cndmask_b32_e64 v191, v190, v204, s[0:1]
	v_lshlrev_b32_e32 v191, 2, v191
	v_xor_b32_e32 v210, 32, v190
	v_cmp_lt_i32_e64 s[0:1], v210, v211
	s_waitcnt vmcnt(0)
	v_lshlrev_b32_e32 v202, 16, v192
	v_and_b32_e32 v203, 0xffff0000, v192
	v_lshlrev_b32_e32 v192, 16, v193
	v_and_b32_e32 v193, 0xffff0000, v193
	v_lshlrev_b32_e32 v206, 16, v196
	v_and_b32_e32 v207, 0xffff0000, v196
	v_lshlrev_b32_e32 v196, 16, v197
	v_and_b32_e32 v197, 0xffff0000, v197
	v_lshlrev_b32_e32 v204, 16, v194
	v_and_b32_e32 v205, 0xffff0000, v194
	v_lshlrev_b32_e32 v194, 16, v195
	v_and_b32_e32 v195, 0xffff0000, v195
	v_lshlrev_b32_e32 v208, 16, v198
	v_and_b32_e32 v209, 0xffff0000, v198
	v_lshlrev_b32_e32 v198, 16, v199
	v_and_b32_e32 v199, 0xffff0000, v199
	v_pk_add_f32 v[126:127], v[126:127], v[192:193]
	v_pk_add_f32 v[124:125], v[124:125], v[202:203]
	v_pk_add_f32 v[118:119], v[118:119], v[196:197]
	v_pk_add_f32 v[116:117], v[116:117], v[206:207]
	v_pk_add_f32 v[122:123], v[122:123], v[194:195]
	v_pk_add_f32 v[120:121], v[120:121], v[204:205]
	v_pk_add_f32 v[192:193], v[114:115], v[198:199]
	v_pk_add_f32 v[194:195], v[112:113], v[208:209]
	v_mul_f32_e32 v114, v125, v125
	v_mul_f32_e32 v115, v127, v127
	v_mul_f32_e32 v196, v117, v117
	v_mul_f32_e32 v197, v119, v119
	v_cvt_pk_bf16_f32 v112, v124, v125
	v_mul_f32_e32 v125, v121, v121
	v_mul_f32_e32 v198, v195, v195
	v_fmac_f32_e32 v114, v124, v124
	v_fmac_f32_e32 v115, v126, v126
	v_fmac_f32_e32 v196, v116, v116
	v_fmac_f32_e32 v197, v118, v118
	v_cvt_pk_bf16_f32 v113, v126, v127
	v_mul_f32_e32 v127, v123, v123
	v_mul_f32_e32 v199, v193, v193
	v_fmac_f32_e32 v125, v120, v120
	v_fmac_f32_e32 v198, v194, v194
	v_add_f32_e32 v114, v114, v115
	v_add_f32_e32 v115, v196, v197
	v_fmac_f32_e32 v127, v122, v122
	v_fmac_f32_e32 v199, v192, v192
	v_add_f32_e32 v114, v125, v114
	v_add_f32_e32 v115, v198, v115
	v_add_f32_e32 v114, v127, v114
	v_add_f32_e32 v115, v199, v115
	v_add_f32_e32 v124, v114, v115
	ds_bpermute_b32 v125, v191, v124
	v_cvt_pk_bf16_f32 v114, v120, v121
	v_cvt_pk_bf16_f32 v115, v122, v123
	global_store_dwordx4 v[200:201], v[112:115], off
	v_cvt_pk_bf16_f32 v116, v116, v117
	v_cvt_pk_bf16_f32 v117, v118, v119
	v_cvt_pk_bf16_f32 v118, v194, v195
	v_cvt_pk_bf16_f32 v119, v192, v193
	global_store_dwordx4 v[200:201], v[116:119], off offset:256
	s_nop 0
	v_cndmask_b32_e64 v112, v190, v210, s[0:1]
	s_waitcnt lgkmcnt(0)
	v_add_f32_e32 v113, v124, v125
	v_lshlrev_b32_e32 v112, 2, v112
	ds_bpermute_b32 v114, v112, v113
	s_and_saveexec_b64 s[0:1], vcc
	s_cbranch_execz .LBB0_2722
	v_lshl_add_u64 v[116:117], v[172:173], 2, s[12:13]
	s_waitcnt lgkmcnt(0)
	v_add_f32_e32 v113, v113, v114
	global_atomic_add_f32 v[116:117], v113, off

; __device__ __forceinline__ int lane_opaque() { int l; asm volatile("v_mbcnt_lo_u32_b32 %0, -1, 0\n\tv_mbcnt_hi_u32_b32 %0, -1, %0" : "=v"(l)); return l; }
; DI v4u pack8(const f4& a, const f4& b) { v4u w; w.x = cvt_pk_bf16(a[0], a[1]); w.y = cvt_pk_bf16(a[2], a[3]); w.z = cvt_pk_bf16(b[0], b[1]); w.w = cvt_pk_bf16(b[2], b[3]); return w; }
;     DI void operator()(f4 (&acc)[2][2][4][2], const Unit& u, int wr, int wc, int fr, int fq) const {
;         { const int ln_ = lane_opaque(); fr = ln_ & 15; fq = ln_ >> 4; }
;         const int row0 = u.pm * BM + wr * 64 + fr, col0 = u.pn * BM + wc * 32 + 8 * fq;
; #pragma unroll
;         for (int ai = 0; ai < 2; ++ai) {
;             f4 b0[4][2], b1[4][2];
;             if constexpr (SRCB) {
;                 v4u bb[4][2];
; #pragma unroll
;                 for (int m = 0; m < 4; ++m)
; #pragma unroll
;                     for (int bj = 0; bj < 2; ++bj) bb[m][bj] = *(const v4u*)(baseb + (size_t)(row0 + ai * HALF + m * 16) * D + col0 + bj * HALF);
;                 asm volatile("" ::: "memory");
; #pragma unroll
;                 for (int m = 0; m < 4; ++m)
; #pragma unroll
;                     for (int bj = 0; bj < 2; ++bj) unpack8(bb[m][bj], b0[m][bj], b1[m][bj]);
;             } else {
; #pragma unroll
;                 for (int m = 0; m < 4; ++m)
; #pragma unroll
;                     for (int bj = 0; bj < 2; ++bj) { const size_t off = (size_t)(row0 + ai * HALF + m * 16) * D + col0 + bj * HALF; b0[m][bj] = *(const f4*)(base + off); b1[m][bj] = *(const f4*)(base + off + 4); }
;                 asm volatile("" ::: "memory");
;             }
; #pragma unroll
;             for (int m = 0; m < 4; ++m) { const int row = row0 + ai * HALF + m * 16; float s = 0.f;
; #pragma unroll
;                 for (int bj = 0; bj < 2; ++bj) { const size_t off = (size_t)row * D + col0 + bj * HALF;
;                     const f4 h0 = b0[m][bj] + acc[ai][bj][m][0], h1 = b1[m][bj] + acc[ai][bj][m][1];
;                     *(v4u*)(outb + off) = pack8(h0, h1);
;                     s += (h0[0] * h0[0] + h0[1] * h0[1]) + (h0[2] * h0[2] + h0[3] * h0[3]) + (h1[0] * h1[0] + h1[1] * h1[1]) + (h1[2] * h1[2] + h1[3] * h1[3]); }
;                 s += __shfl_xor(s, 16); s += __shfl_xor(s, 32);
;                 if (fq == 0) atomicAdd(ss + row, s); }
.LBB0_2938:
	s_lshl_b32 s0, s50, 8
	s_add_i32 s0, s0, s39
	v_mbcnt_lo_u32_b32 v191, -1, 0
	v_mbcnt_hi_u32_b32 v191, -1, v191
	v_xor_b32_e32 v210, 32, v190
	v_and_or_b32 v172, v191, 15, s0
	s_lshl_b32 s0, s49, 8
	v_ashrrev_i32_e32 v128, 1, v191
	s_or_b32 s0, s0, s40
	v_and_b32_e32 v128, -8, v128
	v_add_u32_e32 v168, s0, v128
	v_ashrrev_i32_e32 v169, 31, v168
	v_lshlrev_b64 v[200:201], 1, v[168:169]
	v_ashrrev_i32_e32 v173, 31, v172
	v_lshl_add_u64 v[170:171], s[8:9], 0, v[200:201]
	v_lshlrev_b64 v[202:203], 13, v[172:173]
	v_lshl_add_u64 v[128:129], v[170:171], 0, v[202:203]
	s_mov_b64 s[98:99], 0x100000
	v_lshl_add_u64 v[226:227], v[128:129], 0, s[98:99]
	global_load_dword v228, v[226:227], off
	global_load_dword v229, v[226:227], off offset:256
	global_load_dwordx4 v[192:195], v[128:129], off
	global_load_dwordx4 v[196:199], v[128:129], off offset:256
	v_or_b32_e32 v182, 16, v172
	v_or_b32_e32 v178, 32, v172
	v_or_b32_e32 v174, 48, v172
	v_ashrrev_i32_e32 v183, 31, v182
	v_ashrrev_i32_e32 v179, 31, v178
	v_ashrrev_i32_e32 v175, 31, v174
	v_lshlrev_b64 v[184:185], 13, v[182:183]
	v_lshlrev_b64 v[180:181], 13, v[178:179]
	v_lshlrev_b64 v[176:177], 13, v[174:175]
	v_lshl_add_u64 v[128:129], v[170:171], 0, v[184:185]
	v_lshl_add_u64 v[130:131], v[170:171], 0, v[180:181]
	v_lshl_add_u64 v[204:205], v[170:171], 0, v[176:177]
	v_lshl_add_u64 v[226:227], v[128:129], 0, s[98:99]
	global_load_dword v230, v[226:227], off
	global_load_dword v231, v[226:227], off offset:256
	global_load_dwordx4 v[148:151], v[128:129], off
	global_load_dwordx4 v[144:147], v[128:129], off offset:256
	v_lshl_add_u64 v[226:227], v[130:131], 0, s[98:99]
	global_load_dword v232, v[226:227], off
	global_load_dword v233, v[226:227], off offset:256
	global_load_dwordx4 v[140:143], v[130:131], off
	global_load_dwordx4 v[136:139], v[130:131], off offset:256
	v_lshl_add_u64 v[226:227], v[204:205], 0, s[98:99]
	global_load_dword v234, v[226:227], off
	global_load_dword v235, v[226:227], off offset:256
	global_load_dwordx4 v[132:135], v[204:205], off
	s_nop 0
	global_load_dwordx4 v[128:131], v[204:205], off offset:256
	v_and_b32_e32 v205, 64, v190
	v_xor_b32_e32 v204, 16, v190
	v_add_u32_e32 v211, 64, v205
	v_lshl_add_u64 v[202:203], s[10:11], 0, v[202:203]
	v_cmp_lt_i32_e64 s[0:1], v204, v211
	v_lshl_add_u64 v[200:201], v[202:203], 0, v[200:201]
	v_cmp_gt_u32_e32 vcc, 16, v191
	v_cndmask_b32_e64 v191, v190, v204, s[0:1]
	v_lshlrev_b32_e32 v191, 2, v191
	v_cmp_lt_i32_e64 s[0:1], v210, v211
	s_waitcnt vmcnt(0)
	v_lshlrev_b32_e32 v202, 16, v192
	v_and_b32_e32 v203, 0xffff0000, v192
	v_lshlrev_b32_e32 v192, 16, v193
	v_and_b32_e32 v193, 0xffff0000, v193
	v_lshlrev_b32_e32 v206, 16, v196
	v_and_b32_e32 v207, 0xffff0000, v196
	v_lshlrev_b32_e32 v196, 16, v197
	v_and_b32_e32 v197, 0xffff0000, v197
	v_lshlrev_b32_e32 v204, 16, v194
	v_and_b32_e32 v205, 0xffff0000, v194
	v_lshlrev_b32_e32 v194, 16, v195
	v_and_b32_e32 v195, 0xffff0000, v195
	v_lshlrev_b32_e32 v208, 16, v198
	v_and_b32_e32 v209, 0xffff0000, v198
	v_lshlrev_b32_e32 v198, 16, v199
	v_and_b32_e32 v199, 0xffff0000, v199
	v_pk_add_f32 v[126:127], v[126:127], v[192:193]
	v_pk_add_f32 v[124:125], v[124:125], v[202:203]
	v_pk_add_f32 v[118:119], v[118:119], v[196:197]
	v_pk_add_f32 v[116:117], v[116:117], v[206:207]
	v_pk_add_f32 v[122:123], v[122:123], v[194:195]
	v_pk_add_f32 v[120:121], v[120:121], v[204:205]
	v_pk_add_f32 v[192:193], v[114:115], v[198:199]
	v_pk_add_f32 v[194:195], v[112:113], v[208:209]
	v_mul_f32_e32 v114, v125, v125
	v_mul_f32_e32 v115, v127, v127
	v_mul_f32_e32 v196, v117, v117
	v_mul_f32_e32 v197, v119, v119
	v_cvt_pk_bf16_f32 v112, v124, v125
	v_mul_f32_e32 v125, v121, v121
	v_mul_f32_e32 v198, v195, v195
	v_fmac_f32_e32 v114, v124, v124
	v_fmac_f32_e32 v115, v126, v126
	v_fmac_f32_e32 v196, v116, v116
	v_fmac_f32_e32 v197, v118, v118
	v_cvt_pk_bf16_f32 v113, v126, v127
	v_mul_f32_e32 v127, v123, v123
	v_mul_f32_e32 v199, v193, v193
	v_fmac_f32_e32 v125, v120, v120
	v_fmac_f32_e32 v198, v194, v194
	v_add_f32_e32 v114, v114, v115
	v_add_f32_e32 v115, v196, v197
	v_fmac_f32_e32 v127, v122, v122
	v_fmac_f32_e32 v199, v192, v192
	v_add_f32_e32 v114, v125, v114
	v_add_f32_e32 v115, v198, v115
	v_add_f32_e32 v114, v127, v114
	v_add_f32_e32 v115, v199, v115
	v_add_f32_e32 v124, v114, v115
	ds_bpermute_b32 v125, v191, v124
	v_cvt_pk_bf16_f32 v114, v120, v121
	v_cvt_pk_bf16_f32 v115, v122, v123
	global_store_dwordx4 v[200:201], v[112:115], off
	v_cvt_pk_bf16_f32 v116, v116, v117
	v_cvt_pk_bf16_f32 v117, v118, v119
	v_cvt_pk_bf16_f32 v118, v194, v195
	v_cvt_pk_bf16_f32 v119, v192, v193
	global_store_dwordx4 v[200:201], v[116:119], off offset:256
	s_nop 0
	v_cndmask_b32_e64 v112, v190, v210, s[0:1]
	s_waitcnt lgkmcnt(0)
	v_add_f32_e32 v113, v124, v125
	v_lshlrev_b32_e32 v112, 2, v112
	ds_bpermute_b32 v114, v112, v113
	s_and_saveexec_b64 s[0:1], vcc
	s_cbranch_execz .LBB0_2940
	v_lshl_add_u64 v[116:117], v[172:173], 2, s[12:13]
	s_waitcnt lgkmcnt(0)
	v_add_f32_e32 v113, v113, v114
	global_atomic_add_f32 v[116:117], v113, off
